# scan2 next-batch loads use linear addressing (75 fewer scalar ops per batch)
# speedup vs baseline: 1.0572x; 1.0084x over previous
; __device__ __forceinline__ void scan2_phase(KA a, LAS unsigned char* lds, int G, const int tid, const int bid) {
;     ...
;         const int c = h * 64 + lane;
;         const float mpr = AIN(I_MU_PREV)[c], mnr = AIN(I_MU_NEXT)[c], mpk = AIN(I_MU_PREV)[512 + c], mnk = AIN(I_MU_NEXT)[512 + c], mpv = AIN(I_MU_PREV)[1024 + c], mnv = AIN(I_MU_NEXT)[1024 + c];
;         const float kkc = AIN(I_K_K)[c], kac = AIN(I_K_A)[c];
;         bf16_t* Y = (bf16_t*)(ws + (dir ? WS_YB : WS_YF));
;         f32x4 accS[4];
; #pragma unroll
;         for (int j = 0; j < 4; ++j) accS[j] = (f32x4){0.f, 0.f, 0.f, 0.f};
;         unsigned rawR[6], rawK[6], rawV[6], rawL[4], rawA[4]; float rawS[4];
;         const int nb = len / 16;
;     ...
;         SC2_LOAD(0);
.LBB0_178:
	s_sub_i32 s30, s77, s66
	s_bfe_u32 s29, s29, 0x30001
	s_add_i32 s30, s30, -4
	s_and_b64 s[62:63], s[8:9], exec
	s_cselect_b32 s30, s66, s30
	s_add_i32 s62, s30, -1
	s_add_i32 s78, s77, -1
	s_min_i32 s62, s62, s78
	s_cmp_gt_i32 s30, 0
	s_cselect_b32 s62, s62, 0
	s_add_i32 s62, s62, s76
	s_mul_hi_i32 s63, s62, 0x1b60
	s_mulk_i32 s62, 0x1b60
	s_add_u32 s62, s48, s62
	s_addc_u32 s63, s49, s63
	s_min_i32 s79, s30, s78
	s_add_i32 s79, s79, s76
	s_mul_hi_i32 s81, s79, 0x1b60
	s_mulk_i32 s79, 0x1b60
	s_add_u32 s80, s48, s79
	s_addc_u32 s81, s49, s81
	s_or_b32 s79, s30, 1
	s_min_i32 s79, s79, s78
	v_lshl_or_b32 v0, s29, 6, v77
	s_add_i32 s79, s79, s76
	v_lshlrev_b32_e32 v1, 2, v0
	s_mul_hi_i32 s83, s79, 0x1b60
	s_mulk_i32 s79, 0x1b60
	v_or_b32_e32 v2, 0x1000, v1
	v_lshlrev_b32_e32 v18, 1, v0
	s_add_u32 s82, s48, s79
	s_waitcnt lgkmcnt(0)
	global_load_dword v118, v2, s[24:25]
	global_load_dword v119, v2, s[26:27]
	global_load_dword v120, v1, s[24:25]
	global_load_dword v121, v1, s[26:27]
	global_load_dword v122, v1, s[24:25] offset:2048
	global_load_dword v83, v1, s[26:27] offset:2048
	global_load_dword v123, v1, s[44:45]
	global_load_dword v82, v1, s[46:47]
	s_addc_u32 s83, s49, s83
	global_load_ushort v124, v18, s[62:63]
	global_load_ushort v125, v18, s[62:63] offset:1024
	global_load_ushort v126, v18, s[62:63] offset:2048
	global_load_ushort v127, v18, s[80:81]
	global_load_ushort v128, v18, s[80:81] offset:1024
	global_load_ushort v129, v18, s[80:81] offset:2048
	global_load_ushort v130, v18, s[82:83]
	global_load_ushort v131, v18, s[82:83] offset:1024
	s_or_b32 s62, s30, 2
	s_min_i32 s62, s62, s78
	s_add_i32 s62, s62, s76
	s_mul_hi_i32 s63, s62, 0x1b60
	s_mulk_i32 s62, 0x1b60
	s_add_u32 s62, s48, s62
	s_addc_u32 s63, s49, s63
	s_or_b32 s79, s30, 3
	s_min_i32 s79, s79, s78
	s_add_i32 s79, s79, s76
	s_mul_hi_i32 s81, s79, 0x1b60
	s_mulk_i32 s79, 0x1b60
	s_add_u32 s80, s48, s79
	s_addc_u32 s81, s49, s81
	s_add_i32 s30, s30, 4
	s_min_i32 s30, s30, s78
	s_add_i32 s30, s30, s76
	s_mul_hi_i32 s79, s30, 0x1b60
	s_mulk_i32 s30, 0x1b60
	s_add_u32 s84, s48, s30
	s_addc_u32 s85, s49, s79
	global_load_ushort v136, v18, s[82:83] offset:2048
	global_load_ushort v137, v18, s[62:63]
	global_load_ushort v138, v18, s[62:63] offset:1024
	global_load_ushort v139, v18, s[62:63] offset:2048
	global_load_ushort v140, v18, s[80:81]
	global_load_ushort v141, v18, s[80:81] offset:1024
	global_load_ushort v142, v18, s[80:81] offset:2048
	global_load_ushort v144, v18, s[84:85]
	s_add_i32 s30, s77, s67
	s_lshl_b32 s62, s29, 2
	s_add_u32 s79, s42, s62
	s_addc_u32 s80, s43, 0
	s_and_b64 s[62:63], s[8:9], exec
	s_cselect_b32 s62, s66, s30
	s_add_i32 s62, s62, s76
	s_ashr_i32 s63, s62, 31
	v_or_b32_e32 v0, s68, v0
	s_lshl_b64 s[82:83], s[62:63], 12
	s_lshl_b64 s[62:63], s[62:63], 5
	v_lshlrev_b32_e32 v0, 1, v0
	v_mov_b32_e32 v1, v19
	s_add_u32 s62, s79, s62
	v_lshl_add_u64 v[84:85], s[4:5], 0, v[0:1]
	s_addc_u32 s63, s80, s63
	s_add_i32 s81, s30, -1
	v_lshl_add_u64 v[0:1], v[84:85], 0, s[82:83]
	s_and_b64 s[82:83], s[8:9], exec
	s_cselect_b32 s81, s70, s81
	s_add_i32 s82, s81, s76
	s_ashr_i32 s83, s82, 31
	s_lshl_b64 s[86:87], s[82:83], 12
	s_lshl_b64 s[82:83], s[82:83], 5
	s_add_u32 s82, s79, s82
	s_addc_u32 s83, s80, s83
	s_add_i32 s81, s30, -2
	v_lshl_add_u64 v[2:3], v[84:85], 0, s[86:87]
	s_and_b64 s[86:87], s[8:9], exec
	s_cselect_b32 s81, s71, s81
	s_add_i32 s86, s81, s76
	s_ashr_i32 s87, s86, 31
	s_lshl_b64 s[88:89], s[86:87], 12
	s_lshl_b64 s[86:87], s[86:87], 5
	s_add_u32 s86, s79, s86
	s_addc_u32 s87, s80, s87
	s_add_i32 s30, s30, -3
	v_lshl_add_u64 v[4:5], v[84:85], 0, s[88:89]
	s_and_b64 s[88:89], s[8:9], exec
	s_cselect_b32 s30, s72, s30
	s_add_i32 s88, s30, s76
	s_ashr_i32 s89, s88, 31
	s_lshl_b64 s[90:91], s[88:89], 12
	v_lshl_add_u64 v[6:7], v[84:85], 0, s[90:91]
	global_load_ushort v145, v[0:1], off
	global_load_ushort v147, v[0:1], off offset:2048
	global_load_ushort v150, v[2:3], off
	global_load_ushort v151, v[2:3], off offset:2048
	global_load_ushort v153, v[4:5], off
	global_load_ushort v154, v[4:5], off offset:2048
	global_load_ushort v156, v[6:7], off
	global_load_ushort v157, v[6:7], off offset:2048
	s_lshl_b64 s[88:89], s[88:89], 5
	s_add_u32 s88, s79, s88
	s_addc_u32 s89, s80, s89
	global_load_ushort v146, v18, s[84:85] offset:1024
	global_load_ushort v148, v18, s[84:85] offset:2048
	global_load_dword v149, v19, s[62:63]
	global_load_dword v152, v19, s[82:83]
	global_load_dword v155, v19, s[86:87]
	global_load_dword v158, v19, s[88:89]
	s_lshl_b32 s30, s29, 7
	v_mov_b32_e32 v12, 0
	s_mov_b32 s81, 0
	s_lshr_b32 s82, s77, 4
	v_lshl_add_u64 v[86:87], v[80:81], 0, s[30:31]
	v_lshl_add_u64 v[88:89], s[48:49], 0, v[18:19]
	v_mov_b32_e32 v143, v116
	s_mov_b32 s30, s75
	s_mov_b32 s83, 0
	v_mov_b32_e32 v13, v12
	v_mov_b32_e32 v14, v12
	v_mov_b32_e32 v15, v12
	v_mov_b32_e32 v0, v12
	v_mov_b32_e32 v1, v12
	v_mov_b32_e32 v2, v12
	v_mov_b32_e32 v3, v12
	v_mov_b32_e32 v4, v12
	v_mov_b32_e32 v5, v12
	v_mov_b32_e32 v6, v12
	v_mov_b32_e32 v7, v12
	v_mov_b32_e32 v8, v12
	v_mov_b32_e32 v9, v12
	v_mov_b32_e32 v10, v12
	v_mov_b32_e32 v11, v12
	v_lshlrev_b32_e32 v228, 1, v77
	v_add_u32_e32 v229, 0x1b60, v228
	v_add_u32_e32 v230, 0x1b60, v229
	v_add_u32_e32 v231, 0x1b60, v230
	v_add_u32_e32 v232, 0x1b60, v231
	v_add_u32_e32 v233, 0x1b60, v232
	s_add_i32 s88, s76, s66
	s_and_b64 vcc, exec, s[8:9]
	s_cbranch_vccz .Lscs_dir1
	s_add_i32 s89, s88, 15
	s_add_i32 s90, s88, 16
	v_mov_b32_e32 v234, v228
	v_add_u32_e32 v235, 0x1000, v228
	v_add_u32_e32 v236, 0x2000, v228
	v_add_u32_e32 v237, 0x3000, v228
	v_mov_b32_e32 v238, 0
	v_mov_b32_e32 v239, 32
	v_mov_b32_e32 v240, 64
	v_mov_b32_e32 v241, 0x60
	s_mov_b32 s91, 0
	s_branch .Lscs_join
.Lscs_dir1:
	s_add_i32 s88, s76, s77
	s_sub_i32 s88, s88, s66
	s_add_i32 s89, s88, -21
	s_add_i32 s90, s88, -20
	v_add_u32_e32 v234, 0x3000, v228
	v_add_u32_e32 v235, 0x2000, v228
	v_add_u32_e32 v236, 0x1000, v228
	v_mov_b32_e32 v237, v228
	v_mov_b32_e32 v238, 0x60
	v_mov_b32_e32 v239, 64
	v_mov_b32_e32 v240, 32
	v_mov_b32_e32 v241, 0
	s_movk_i32 s91, 0x400
.Lscs_join:
	s_lshl_b32 s92, s29, 7
	s_mul_i32 s89, s89, 0x1b60
	s_add_u32 s94, s48, s89
	s_addc_u32 s95, s49, 0
	s_add_u32 s94, s94, s92
	s_addc_u32 s95, s95, 0
	s_lshl_b32 s89, s90, 12
	s_add_u32 s96, s4, s89
	s_addc_u32 s97, s5, 0
	s_add_i32 s92, s92, s91
	s_add_u32 s96, s96, s92
	s_addc_u32 s97, s97, 0
	s_lshl_b32 s89, s90, 5
	s_add_u32 s98, s79, s89
	s_addc_u32 s99, s80, 0
	s_branch .LBB0_181

.LBB0_183:
	global_load_ushort v124, v228, s[94:95]
	global_load_ushort v125, v228, s[94:95] offset:1024
	global_load_ushort v126, v228, s[94:95] offset:2048
	global_load_ushort v127, v229, s[94:95]
	global_load_ushort v128, v229, s[94:95] offset:1024
	global_load_ushort v129, v229, s[94:95] offset:2048
	global_load_ushort v130, v230, s[94:95]
	global_load_ushort v131, v230, s[94:95] offset:1024
	global_load_ushort v136, v230, s[94:95] offset:2048
	global_load_ushort v137, v231, s[94:95]
	global_load_ushort v138, v231, s[94:95] offset:1024
	global_load_ushort v139, v231, s[94:95] offset:2048
	global_load_ushort v140, v232, s[94:95]
	global_load_ushort v141, v232, s[94:95] offset:1024
	global_load_ushort v142, v232, s[94:95] offset:2048
	global_load_ushort v144, v233, s[94:95]
	global_load_ushort v146, v233, s[94:95] offset:1024
	global_load_ushort v148, v233, s[94:95] offset:2048
	global_load_ushort v145, v234, s[96:97]
	global_load_ushort v147, v234, s[96:97] offset:2048
	global_load_dword v149, v238, s[98:99]
	global_load_ushort v150, v235, s[96:97]
	global_load_ushort v151, v235, s[96:97] offset:2048
	global_load_dword v152, v239, s[98:99]
	global_load_ushort v153, v236, s[96:97]
	global_load_ushort v154, v236, s[96:97] offset:2048
	global_load_dword v155, v240, s[98:99]
	global_load_ushort v156, v237, s[96:97]
	global_load_ushort v157, v237, s[96:97] offset:2048
	global_load_dword v158, v241, s[98:99]
	s_and_b64 vcc, exec, s[8:9]
	s_cbranch_vccz .Lsc_adv_dir1
	s_add_u32 s94, s94, 0x1b600
	s_addc_u32 s95, s95, 0
	s_add_u32 s96, s96, 0x10000
	s_addc_u32 s97, s97, 0
	s_add_u32 s98, s98, 0x200
	s_addc_u32 s99, s99, 0
	s_branch .LBB0_184
.Lsc_adv_dir1:
	s_sub_u32 s94, s94, 0x1b600
	s_subb_u32 s95, s95, 0
	s_sub_u32 s96, s96, 0x10000
	s_subb_u32 s97, s97, 0
	s_sub_u32 s98, s98, 0x200
	s_subb_u32 s99, s99, 0
